# weight-conversion loop with counted vmcnt waits (next item's prefetch stays in flight during the transpose); on top of v61
# baseline (speedup 1.0000x reference)
; __device__ __forceinline__ ConvItem conv_decode(const Args& a, int it) {
;     unsigned char* ws = a.ws; const float* W; bf16_t* WT; int K, N, mode = 0;
;     if (it < 4 * 1024) { const int m = it >> 10; it &= 1023; const int jj = m >> 1; mode = 1 + (m & 1); W = a.in[15 + (m & 1)] + (size_t)jj * D * D; WT = (bf16_t*)(ws + WS_WSSM) + (size_t)jj * 4096 * D; K = D; N = D; }
;     else if ((it -= 4 * 1024) < 3072) { W = a.in[17]; WT = (bf16_t*)(ws + WS_WQKV); K = D; N = 3 * D; }
;     else if ((it -= 3072) < 1024) { W = a.in[19]; WT = (bf16_t*)(ws + WS_WAO); K = D; N = D; }
;     else if ((it -= 1024) < 4096) { W = a.in[20]; WT = (bf16_t*)(ws + WS_WHIN); K = D; N = 4 * D; }
;     else if ((it -= 4096) < 1024) { W = a.in[23]; WT = (bf16_t*)(ws + WS_WHO); K = D; N = D; }
;     else if ((it -= 1024) < 4 * 4096) { const int l = it >> 12; it &= 4095; W = a.in[28] + (size_t)l * D * FF; WT = (bf16_t*)(ws + WS_WF1) + (size_t)l * FF * D; K = D; N = FF; }
;     else { it -= 4 * 4096; const int l = it >> 12; it &= 4095; W = a.in[29] + (size_t)l * FF * D; WT = (bf16_t*)(ws + WS_WF2) + (size_t)l * D * FF; K = FF; N = D; }
;     const int nb = N / 64, kb = it / nb, n0 = 64 * (it - kb * nb), k0 = 64 * kb;
;     const int row0 = mode == 0 ? n0 : 256 * (n0 >> 7) + 128 * (mode - 1) + (n0 & 127);
;     ConvItem c; c.src = W + (size_t)k0 * N + n0; c.dst = WT + ((size_t)(row0 >> 8) * (K / 64) + kb) * 16384; c.N = N; c.K = K; c.w0 = row0 & 255; c.adj = mode == 0; return c;
.LBB0_155:
	s_lshr_b32 s5, s12, 6
	v_cvt_f32_u32_e32 v2, s5
	v_cvt_f32_u32_e32 v3, s13
	s_lshl_b32 s42, s89, 2
	v_lshrrev_b32_e32 v131, 4, v130
	v_rcp_iflag_f32_e32 v4, v2
	v_mov_b32_e32 v135, 0
	v_or_b32_e32 v133, 4, v131
	v_or_b32_e32 v146, 8, v131
	v_mul_f32_e32 v4, v3, v4
	v_trunc_f32_e32 v4, v4
	v_cvt_u32_f32_e32 v5, v4
	v_fma_f32 v3, -v4, v2, v3
	v_cmp_ge_f32_e64 s[14:15], |v3|, v2
	s_cmp_lg_u64 s[14:15], 0
	v_readfirstlane_b32 s2, v5
	s_addc_u32 s2, s2, 0
	s_and_b32 s2, s2, 0xffff
	s_mul_i32 s5, s5, s2
	s_sub_i32 s5, s13, s5
	s_lshl_b32 s14, s5, 6
	s_lshl_b32 s5, s5, 7
	s_lshl_b32 s15, s4, 7
	s_and_b32 s5, s5, 0xffffff00
	s_and_b32 s13, s14, 64
	s_add_i32 s15, s15, s5
	s_or_b32 s5, s15, s13
	s_add_i32 s13, s5, 0xffffff80
	s_cmp_eq_u32 s4, 0
	s_cselect_b64 s[4:5], -1, 0
	v_cndmask_b32_e64 v175, 0, 1, s[4:5]
	s_and_b64 s[4:5], s[4:5], exec
	s_cselect_b32 s13, s14, s13
	s_lshl_b32 s4, s2, 6
	s_mul_hi_u32 s5, s4, s12
	s_mul_i32 s4, s4, s12
	s_lshl_b64 s[4:5], s[4:5], 2
	s_waitcnt lgkmcnt(0)
; #define LAS __attribute__((address_space(3)))
; __device__ __forceinline__ unsigned pk2(float lo, float hi) { const f32x2 v = {lo, hi}; return __builtin_bit_cast(unsigned, __builtin_convertvector(v, bf16x2_t)); }
; __device__ __forceinline__ ConvItem conv_decode(const Args& a, int it) {
;     ...
;     const int nb = N / 64, kb = it / nb, n0 = 64 * (it - kb * nb), k0 = 64 * kb;
;     const int row0 = mode == 0 ? n0 : 256 * (n0 >> 7) + 128 * (mode - 1) + (n0 & 127);
;     ConvItem c; c.src = W + (size_t)k0 * N + n0; c.dst = WT + ((size_t)(row0 >> 8) * (K / 64) + kb) * 16384; c.N = N; c.K = K; c.w0 = row0 & 255; c.adj = mode == 0; return c;
; }
; __device__ __forceinline__ void conv_load(const ConvItem& c, f32x4 (&wv)[16], int lane) {
; #pragma unroll
;     for (int i = 0; i < 16; ++i) wv[i] = __builtin_nontemporal_load((const f32x4*)(c.src + (size_t)(4 * i + (lane >> 4)) * c.N + 4 * (lane & 15)));
; }
; __device__ __forceinline__ void conv_store(const ConvItem& c, const f32x4 (&wv)[16], LAS float* scr, int lane) {
; #pragma unroll
;     for (int i = 0; i < 16; ++i) { LAS float* d = scr + (4 * i + (lane >> 4)) * 65 + 4 * (lane & 15); d[0] = wv[i][0]; d[1] = wv[i][1]; d[2] = wv[i][2]; d[3] = wv[i][3]; }
;     asm volatile("s_waitcnt lgkmcnt(0)" ::: "memory");
;     const int cc = lane & 7;
; #pragma unroll
;     for (int j = 0; j < 8; ++j) { const int n = (lane >> 3) + 8 * j; const LAS float* sp = scr + (8 * cc) * 65 + n;
;         u32x4 o; o.x = pk2(sp[0 * 65], sp[1 * 65]); o.y = pk2(sp[2 * 65], sp[3 * 65]); o.z = pk2(sp[4 * 65], sp[5 * 65]); o.w = pk2(sp[6 * 65], sp[7 * 65]);
;         *(u32x4*)(c.dst + conv_rowoff(c.w0 + n, c.adj) + 8 * cc) = o; }
;     asm volatile("s_waitcnt lgkmcnt(0)" ::: "memory");
; }
; __device__ __forceinline__ void conv_worker(const Args& a, LAS float* scr, int w, int nw, int lane) {
;     f32x4 va[16], vb[16];
;     int it = w; if (it >= CONV_ITEMS) return;
;     ConvItem ca = conv_decode(a, it), cb = ca; conv_load(ca, va, lane);
;     for (;;) {
;         const bool hb = it + nw < CONV_ITEMS; if (hb) { cb = conv_decode(a, it + nw); conv_load(cb, vb, lane); }
	s_add_u32 s10, s10, s4
	s_addc_u32 s11, s11, s5
	s_ashr_i32 s15, s14, 31
	s_lshl_b64 s[4:5], s[14:15], 2
	v_lshlrev_b32_e32 v2, 2, v130
	s_add_u32 s10, s10, s4
	v_and_b32_e32 v132, 60, v2
	v_mul_u32_u24_e32 v2, s12, v131
	s_addc_u32 s11, s11, s5
	v_lshlrev_b32_e32 v134, 2, v2
	v_lshl_add_u64 v[2:3], s[10:11], 0, v[134:135]
	v_lshlrev_b32_e32 v134, 2, v132
	v_lshl_add_u64 v[10:11], v[2:3], 0, v[134:135]
	v_mul_u32_u24_e32 v2, s12, v133
	v_lshlrev_b32_e32 v2, 2, v2
	v_mov_b32_e32 v3, v135
	v_lshl_add_u64 v[2:3], s[10:11], 0, v[2:3]
	v_lshl_add_u64 v[12:13], v[2:3], 0, v[134:135]
	global_load_dwordx4 v[2:5], v[10:11], off nt
	global_load_dwordx4 v[6:9], v[12:13], off nt
	v_mul_u32_u24_e32 v10, s12, v146
	v_lshlrev_b32_e32 v10, 2, v10
	v_mov_b32_e32 v11, v135
	v_lshl_add_u64 v[10:11], s[10:11], 0, v[10:11]
	v_or_b32_e32 v147, 12, v131
	v_lshl_add_u64 v[18:19], v[10:11], 0, v[134:135]
	v_mul_u32_u24_e32 v10, s12, v147
	v_lshlrev_b32_e32 v10, 2, v10
	v_mov_b32_e32 v11, v135
	v_lshl_add_u64 v[10:11], s[10:11], 0, v[10:11]
	v_or_b32_e32 v148, 16, v131
	v_lshl_add_u64 v[20:21], v[10:11], 0, v[134:135]
	global_load_dwordx4 v[10:13], v[18:19], off nt
	global_load_dwordx4 v[14:17], v[20:21], off nt
	v_mul_u32_u24_e32 v18, s12, v148
	v_lshlrev_b32_e32 v18, 2, v18
	v_mov_b32_e32 v19, v135
	v_lshl_add_u64 v[18:19], s[10:11], 0, v[18:19]
	v_or_b32_e32 v149, 20, v131
	v_lshl_add_u64 v[26:27], v[18:19], 0, v[134:135]
	v_mul_u32_u24_e32 v18, s12, v149
	v_lshlrev_b32_e32 v18, 2, v18
	v_mov_b32_e32 v19, v135
	v_lshl_add_u64 v[18:19], s[10:11], 0, v[18:19]
	v_or_b32_e32 v150, 24, v131
	v_lshl_add_u64 v[28:29], v[18:19], 0, v[134:135]
	global_load_dwordx4 v[18:21], v[26:27], off nt
	global_load_dwordx4 v[22:25], v[28:29], off nt
	v_mul_u32_u24_e32 v26, s12, v150
	v_lshlrev_b32_e32 v26, 2, v26
	v_mov_b32_e32 v27, v135
	v_lshl_add_u64 v[26:27], s[10:11], 0, v[26:27]
	v_or_b32_e32 v151, 28, v131
	v_lshl_add_u64 v[34:35], v[26:27], 0, v[134:135]
	v_mul_u32_u24_e32 v26, s12, v151
	v_lshlrev_b32_e32 v26, 2, v26
	v_mov_b32_e32 v27, v135
	v_lshl_add_u64 v[26:27], s[10:11], 0, v[26:27]
	v_or_b32_e32 v152, 32, v131
	v_lshl_add_u64 v[36:37], v[26:27], 0, v[134:135]
	global_load_dwordx4 v[26:29], v[34:35], off nt
	global_load_dwordx4 v[30:33], v[36:37], off nt
	v_mul_u32_u24_e32 v34, s12, v152
	v_lshlrev_b32_e32 v34, 2, v34
	v_mov_b32_e32 v35, v135
	v_lshl_add_u64 v[34:35], s[10:11], 0, v[34:35]
	v_or_b32_e32 v153, 36, v131
	v_lshl_add_u64 v[42:43], v[34:35], 0, v[134:135]
	v_mul_u32_u24_e32 v34, s12, v153
	v_lshlrev_b32_e32 v34, 2, v34
	v_mov_b32_e32 v35, v135
	v_lshl_add_u64 v[34:35], s[10:11], 0, v[34:35]
	v_or_b32_e32 v154, 40, v131
	v_lshl_add_u64 v[44:45], v[34:35], 0, v[134:135]
	global_load_dwordx4 v[34:37], v[42:43], off nt
	global_load_dwordx4 v[38:41], v[44:45], off nt
	v_mul_u32_u24_e32 v42, s12, v154
	v_lshlrev_b32_e32 v42, 2, v42
	v_mov_b32_e32 v43, v135
	v_lshl_add_u64 v[42:43], s[10:11], 0, v[42:43]
	v_or_b32_e32 v155, 44, v131
	v_lshl_add_u64 v[50:51], v[42:43], 0, v[134:135]
	v_mul_u32_u24_e32 v42, s12, v155
	v_lshlrev_b32_e32 v42, 2, v42
	v_mov_b32_e32 v43, v135
	v_lshl_add_u64 v[42:43], s[10:11], 0, v[42:43]
	v_or_b32_e32 v156, 48, v131
	v_lshl_add_u64 v[52:53], v[42:43], 0, v[134:135]
	global_load_dwordx4 v[42:45], v[50:51], off nt
	global_load_dwordx4 v[46:49], v[52:53], off nt
	v_mul_u32_u24_e32 v50, s12, v156
	v_lshlrev_b32_e32 v50, 2, v50
	v_mov_b32_e32 v51, v135
	v_lshl_add_u64 v[50:51], s[10:11], 0, v[50:51]
	v_or_b32_e32 v157, 52, v131
	v_lshl_add_u64 v[58:59], v[50:51], 0, v[134:135]
	v_mul_u32_u24_e32 v50, s12, v157
	v_lshlrev_b32_e32 v50, 2, v50
	v_mov_b32_e32 v51, v135
	v_lshl_add_u64 v[50:51], s[10:11], 0, v[50:51]
	v_or_b32_e32 v158, 56, v131
	v_lshl_add_u64 v[60:61], v[50:51], 0, v[134:135]
	global_load_dwordx4 v[50:53], v[58:59], off nt
	global_load_dwordx4 v[54:57], v[60:61], off nt
	v_mul_u32_u24_e32 v58, s12, v158
	v_or_b32_e32 v159, 60, v131
	v_lshlrev_b32_e32 v58, 2, v58
	v_mov_b32_e32 v59, v135
	v_mul_u32_u24_e32 v60, s12, v159
	v_lshl_add_u64 v[58:59], s[10:11], 0, v[58:59]
	v_lshlrev_b32_e32 v60, 2, v60
	v_mov_b32_e32 v61, v135
	v_lshl_add_u64 v[58:59], v[58:59], 0, v[134:135]
	v_lshl_add_u64 v[60:61], s[10:11], 0, v[60:61]
	v_lshl_add_u64 v[60:61], v[60:61], 0, v[134:135]
	global_load_dwordx4 v[74:77], v[58:59], off nt
	global_load_dwordx4 v[78:81], v[60:61], off nt
	s_ashr_i32 s4, s13, 8
	s_ashr_i32 s5, s4, 31
	s_mul_i32 s5, s8, s5
	s_mul_hi_u32 s10, s8, s4
	s_add_i32 s5, s10, s5
	s_mul_i32 s9, s9, s4
	s_add_i32 s5, s5, s9
	s_mul_i32 s4, s8, s4
	s_add_u32 s4, s4, s2
	s_addc_u32 s5, s5, 0
	s_lshl_b64 s[4:5], s[4:5], 15
	s_add_u32 s30, s6, s4
	s_addc_u32 s31, s7, s5
	s_and_b32 s52, s13, 0xc0
	s_add_u32 s43, s68, 0xe900000
	s_addc_u32 s44, s69, 0
	s_add_u32 s45, s68, 0x6900000
	s_addc_u32 s46, s69, 0
	s_add_u32 s22, s68, 0x6100000
	s_addc_u32 s23, s69, 0
	s_add_u32 s24, s68, 0x4100000
	s_load_dwordx2 s[10:11], s[86:87], 0x88
	s_load_dwordx4 s[12:15], s[86:87], 0x98
	s_load_dwordx4 s[16:19], s[86:87], 0xe0
	s_load_dwordx2 s[20:21], s[86:87], 0xb8
	s_addc_u32 s25, s69, 0
	s_add_u32 s26, s68, 0x3900000
	s_addc_u32 s27, s69, 0
	v_lshlrev_b32_e32 v58, 3, v130
	s_add_u32 s28, s68, 0x2100000
	v_lshrrev_b32_e32 v160, 3, v130
	v_and_b32_e32 v58, 56, v58
	s_addc_u32 s29, s69, 0
	v_add_u32_e32 v59, s33, v134
	v_mul_u32_u24_e32 v60, 0x104, v131
	v_mul_u32_u24_e32 v61, 0x104, v58
	v_lshlrev_b32_e32 v161, 2, v160
	s_add_u32 s47, s68, 0x100000
	v_add3_u32 v162, s33, v61, v161
	v_or_b32_e32 v163, 32, v160
	v_or_b32_e32 v164, 40, v160
	v_or_b32_e32 v165, 48, v160
	v_or_b32_e32 v166, 56, v160
	v_and_b32_e32 v167, 16, v161
	v_bitop3_b32 v168, v161, 19, v160 bitop3:0xc8
	s_addc_u32 s48, s69, 0
	s_lshl_b32 s49, s89, 3
	s_movk_i32 s50, 0x43
	v_lshlrev_b32_e32 v136, 1, v58
	s_movk_i32 s51, 0x63
	v_add_u32_e32 v169, v59, v60
	v_mov_b32_e32 v170, 0x43
	v_mov_b32_e32 v171, 0x100
	v_mov_b32_e32 v172, 0x200
	v_mov_b32_e32 v173, 0x300
	v_mov_b32_e32 v174, 0x63
	s_mov_b32 s40, s52
	s_mov_b64 s[34:35], s[30:31]
	v_mov_b32_e32 v176, v175
	s_waitcnt vmcnt(0)
	s_branch .LBB0_157

; #define LAS __attribute__((address_space(3)))
; __device__ __forceinline__ unsigned pk2(float lo, float hi) { const f32x2 v = {lo, hi}; return __builtin_bit_cast(unsigned, __builtin_convertvector(v, bf16x2_t)); }
; __device__ __forceinline__ void conv_store(const ConvItem& c, const f32x4 (&wv)[16], LAS float* scr, int lane) {
; #pragma unroll
;     for (int i = 0; i < 16; ++i) { LAS float* d = scr + (4 * i + (lane >> 4)) * 65 + 4 * (lane & 15); d[0] = wv[i][0]; d[1] = wv[i][1]; d[2] = wv[i][2]; d[3] = wv[i][3]; }
;     asm volatile("s_waitcnt lgkmcnt(0)" ::: "memory");
;     const int cc = lane & 7;
; #pragma unroll
;     for (int j = 0; j < 8; ++j) { const int n = (lane >> 3) + 8 * j; const LAS float* sp = scr + (8 * cc) * 65 + n;
;         u32x4 o; o.x = pk2(sp[0 * 65], sp[1 * 65]); o.y = pk2(sp[2 * 65], sp[3 * 65]); o.z = pk2(sp[4 * 65], sp[5 * 65]); o.w = pk2(sp[6 * 65], sp[7 * 65]);
;         *(u32x4*)(c.dst + conv_rowoff(c.w0 + n, c.adj) + 8 * cc) = o; }
.LBB0_182:
	v_add_u32_e32 v178, 0x410, v169
	v_add_u32_e32 v179, 0x418, v169
	v_add_u32_e32 v180, 0x820, v169
	v_add_u32_e32 v181, 0x828, v169
	v_add_u32_e32 v182, 0xc30, v169
	v_add_u32_e32 v183, 0xc38, v169
	v_add_u32_e32 v184, 0x1040, v169
	v_add_u32_e32 v185, 0x1048, v169
	v_add_u32_e32 v186, 0x1450, v169
	v_add_u32_e32 v187, 0x1458, v169
	v_add_u32_e32 v188, 0x1860, v169
	v_add_u32_e32 v189, 0x1868, v169
	v_add_u32_e32 v190, 0x1c70, v169
	v_add_u32_e32 v191, 0x1c78, v169
	v_add_u32_e32 v192, 0x2080, v169
	v_add_u32_e32 v193, 0x2088, v169
	v_add_u32_e32 v194, 0x2490, v169
	v_add_u32_e32 v195, 0x2498, v169
	v_add_u32_e32 v196, 0x28a0, v169
	v_add_u32_e32 v197, 0x28a8, v169
	v_add_u32_e32 v198, 0x2cb0, v169
	v_add_u32_e32 v199, 0x2cb8, v169
	v_add_u32_e32 v200, 0x30c0, v169
	v_add_u32_e32 v201, 0x30c8, v169
	v_add_u32_e32 v202, 0x34d0, v169
	v_add_u32_e32 v203, 0x34d8, v169
	v_add_u32_e32 v204, 0x38e0, v169
	v_add_u32_e32 v205, 0x38e8, v169
	v_add_u32_e32 v206, 0x3cf0, v169
	v_add_u32_e32 v207, 0x3cf8, v169
	s_waitcnt vmcnt(39)
	ds_write2_b32 v169, v2, v3 offset1:1
	ds_write2_b32 v169, v4, v5 offset0:2 offset1:3
	s_waitcnt vmcnt(38)
	ds_write2_b32 v178, v6, v7 offset1:1
	ds_write2_b32 v179, v8, v9 offset1:1
	s_waitcnt vmcnt(37)
	ds_write2_b32 v180, v10, v11 offset1:1
	ds_write2_b32 v181, v12, v13 offset1:1
	s_waitcnt vmcnt(36)
	ds_write2_b32 v182, v14, v15 offset1:1
	ds_write2_b32 v183, v16, v17 offset1:1
	s_waitcnt vmcnt(35)
	ds_write2_b32 v184, v18, v19 offset1:1
	ds_write2_b32 v185, v20, v21 offset1:1
	s_waitcnt vmcnt(34)
	ds_write2_b32 v186, v22, v23 offset1:1
	ds_write2_b32 v187, v24, v25 offset1:1
	s_waitcnt vmcnt(33)
	ds_write2_b32 v188, v26, v27 offset1:1
	ds_write2_b32 v189, v28, v29 offset1:1
	s_waitcnt vmcnt(32)
	ds_write2_b32 v190, v30, v31 offset1:1
	ds_write2_b32 v191, v32, v33 offset1:1
	s_waitcnt vmcnt(31)
	ds_write2_b32 v192, v34, v35 offset1:1
	ds_write2_b32 v193, v36, v37 offset1:1
	s_waitcnt vmcnt(30)
	ds_write2_b32 v194, v38, v39 offset1:1
	ds_write2_b32 v195, v40, v41 offset1:1
	s_waitcnt vmcnt(29)
	ds_write2_b32 v196, v42, v43 offset1:1
	ds_write2_b32 v197, v44, v45 offset1:1
	s_waitcnt vmcnt(28)
	ds_write2_b32 v198, v46, v47 offset1:1
	ds_write2_b32 v199, v48, v49 offset1:1
	s_waitcnt vmcnt(27)
	ds_write2_b32 v200, v50, v51 offset1:1
	ds_write2_b32 v201, v52, v53 offset1:1
	s_waitcnt vmcnt(26)
	ds_write2_b32 v202, v54, v55 offset1:1
	ds_write2_b32 v203, v56, v57 offset1:1
	s_waitcnt vmcnt(25)
	ds_write2_b32 v204, v74, v75 offset1:1
	ds_write2_b32 v205, v76, v77 offset1:1
	s_waitcnt vmcnt(24)
	ds_write2_b32 v206, v78, v79 offset1:1
	ds_write2_b32 v207, v80, v81 offset1:1
	s_waitcnt lgkmcnt(0)
	v_add_u32_e32 v177, 0x400, v162
	ds_read2_b32 v[138:139], v162 offset1:65
	ds_read2_b32 v[140:141], v162 offset0:130 offset1:195
	ds_read2_b32 v[142:143], v177 offset0:4 offset1:69
	ds_read2_b32 v[144:145], v177 offset0:134 offset1:199
	v_cmp_eq_u32_e32 vcc, 0, v175
	v_cmp_ne_u32_e64 s[8:9], 0, v175
	s_cbranch_vccnz .LBB0_184
	s_lshr_b32 s2, s52, 1
	v_or_b32_e32 v134, s2, v168
	s_mov_b64 s[4:5], 0
	s_branch .LBB0_185

; #define LAS __attribute__((address_space(3)))
; __device__ __forceinline__ unsigned pk2(float lo, float hi) { const f32x2 v = {lo, hi}; return __builtin_bit_cast(unsigned, __builtin_convertvector(v, bf16x2_t)); }
; __device__ __forceinline__ void conv_store(const ConvItem& c, const f32x4 (&wv)[16], LAS float* scr, int lane) {
; #pragma unroll
;     for (int i = 0; i < 16; ++i) { LAS float* d = scr + (4 * i + (lane >> 4)) * 65 + 4 * (lane & 15); d[0] = wv[i][0]; d[1] = wv[i][1]; d[2] = wv[i][2]; d[3] = wv[i][3]; }
;     asm volatile("s_waitcnt lgkmcnt(0)" ::: "memory");
;     const int cc = lane & 7;
; #pragma unroll
;     for (int j = 0; j < 8; ++j) { const int n = (lane >> 3) + 8 * j; const LAS float* sp = scr + (8 * cc) * 65 + n;
;         u32x4 o; o.x = pk2(sp[0 * 65], sp[1 * 65]); o.y = pk2(sp[2 * 65], sp[3 * 65]); o.z = pk2(sp[4 * 65], sp[5 * 65]); o.w = pk2(sp[6 * 65], sp[7 * 65]);
;         *(u32x4*)(c.dst + conv_rowoff(c.w0 + n, c.adj) + 8 * cc) = o; }
.LBB0_242:
	s_waitcnt vmcnt(39)
	ds_write2_b32 v169, v62, v63 offset1:1
	ds_write2_b32 v169, v64, v65 offset0:2 offset1:3
	s_waitcnt vmcnt(38)
	ds_write2_b32 v178, v58, v59 offset1:1
	ds_write2_b32 v179, v60, v61 offset1:1
	s_waitcnt vmcnt(37)
	ds_write2_b32 v180, v70, v71 offset1:1
	ds_write2_b32 v181, v72, v73 offset1:1
	s_waitcnt vmcnt(36)
	ds_write2_b32 v182, v66, v67 offset1:1
	ds_write2_b32 v183, v68, v69 offset1:1
	s_waitcnt vmcnt(35)
	ds_write2_b32 v184, v86, v87 offset1:1
	ds_write2_b32 v185, v88, v89 offset1:1
	s_waitcnt vmcnt(34)
	ds_write2_b32 v186, v82, v83 offset1:1
	ds_write2_b32 v187, v84, v85 offset1:1
	s_waitcnt vmcnt(33)
	ds_write2_b32 v188, v94, v95 offset1:1
	ds_write2_b32 v189, v96, v97 offset1:1
	s_waitcnt vmcnt(32)
	ds_write2_b32 v190, v90, v91 offset1:1
	ds_write2_b32 v191, v92, v93 offset1:1
	s_waitcnt vmcnt(31)
	ds_write2_b32 v192, v102, v103 offset1:1
	ds_write2_b32 v193, v104, v105 offset1:1
	s_waitcnt vmcnt(30)
	ds_write2_b32 v194, v98, v99 offset1:1
	ds_write2_b32 v195, v100, v101 offset1:1
	s_waitcnt vmcnt(29)
	ds_write2_b32 v196, v110, v111 offset1:1
	ds_write2_b32 v197, v112, v113 offset1:1
	s_waitcnt vmcnt(28)
	ds_write2_b32 v198, v106, v107 offset1:1
	ds_write2_b32 v199, v108, v109 offset1:1
	s_waitcnt vmcnt(27)
	ds_write2_b32 v200, v118, v119 offset1:1
	ds_write2_b32 v201, v120, v121 offset1:1
	s_waitcnt vmcnt(26)
	ds_write2_b32 v202, v114, v115 offset1:1
	ds_write2_b32 v203, v116, v117 offset1:1
	s_waitcnt vmcnt(25)
	ds_write2_b32 v204, v126, v127 offset1:1
	ds_write2_b32 v205, v128, v129 offset1:1
	s_waitcnt vmcnt(24)
	ds_write2_b32 v206, v122, v123 offset1:1
	ds_write2_b32 v207, v124, v125 offset1:1
	s_waitcnt lgkmcnt(0)
	ds_read2_b32 v[138:139], v162 offset1:65
	ds_read2_b32 v[140:141], v162 offset0:130 offset1:195
	ds_read2_b32 v[142:143], v177 offset0:4 offset1:69
	ds_read2_b32 v[144:145], v177 offset0:134 offset1:199
	v_cmp_eq_u32_e32 vcc, 0, v176
	v_cmp_ne_u32_e64 s[8:9], 0, v176
	s_cbranch_vccnz .LBB0_244
	s_lshr_b32 s2, s40, 1
	v_or_b32_e32 v134, s2, v168
	s_mov_b64 s[4:5], 0
	s_branch .LBB0_245

; #define LAS __attribute__((address_space(3)))
; __device__ __forceinline__ void conv_worker(const Args& a, LAS float* scr, int w, int nw, int lane) {
;     f32x4 va[16], vb[16];
;     int it = w; if (it >= CONV_ITEMS) return;
;     ConvItem ca = conv_decode(a, it), cb = ca; conv_load(ca, va, lane);
;     for (;;) {
;         const bool hb = it + nw < CONV_ITEMS; if (hb) { cb = conv_decode(a, it + nw); conv_load(cb, vb, lane); }
;         conv_store(ca, va, scr, lane); if (!hb) break; it += nw;
;         const bool ha = it + nw < CONV_ITEMS; if (ha) { ca = conv_decode(a, it + nw); conv_load(ca, va, lane); }
;         conv_store(cb, vb, scr, lane); if (!ha) break; it += nw;
;     }
.Lconv_drain1:
	s_waitcnt vmcnt(0)
	s_branch .LBB0_182
